# lever 2 (prologue de-serialisation): diff attention unit requests its first K/V tile together with the Q rows, counted vmcnt 11..4 on the Q parking ladder
# baseline (speedup 1.0000x reference)
.LBB0_524:
	s_or_b64 exec, exec, s[20:21]
	s_mul_hi_i32 s11, s25, 0x55555555
	s_sub_i32 s11, s11, s25
	s_lshr_b32 s18, s11, 31
	s_ashr_i32 s20, s11, 1
	s_add_i32 s20, s20, s18
	s_add_i32 s24, s20, 15
	s_waitcnt lgkmcnt(0)
	s_add_u32 s18, s14, 0x16200000
	s_addc_u32 s19, s15, 0
	s_ashr_i32 s28, s4, 6
	s_and_b32 s23, s28, 3
	s_lshl_b32 s11, s24, 7
	s_lshl_b32 s21, s23, 5
	s_or_b32 s26, s21, s11
	s_ashr_i32 s11, s10, 31
	s_mulk_i32 s28, 0x2200
	s_lshl_b64 s[14:15], s[10:11], 11
	s_add_i32 s11, s28, 0
	s_add_i32 s11, s11, 0x13000
	v_and_b32_e32 v1, 31, v0
	v_bfe_u32 v239, v0, 5, 1
	v_mov_b32_e32 v3, s11
	v_or_b32_e32 v2, s26, v1
	v_mad_u32_u24 v3, v1, s95, v3
	v_lshlrev_b32_e32 v192, 4, v239
	v_add_u32_e32 v240, v3, v192
	v_ashrrev_i32_e32 v3, 31, v2
	v_lshl_add_u64 v[200:201], s[14:15], 0, v[2:3]
	v_mov_b64_e32 v[2:3], s[18:19]
	v_mad_u64_u32 v[2:3], s[14:15], v200, s55, v[2:3]
	s_lshl_b32 s14, s27, 7
	v_mad_i32_i24 v3, v201, s55, v3
	s_ashr_i32 s15, s14, 31
	v_lshl_add_u64 v[2:3], s[14:15], 1, v[2:3]
	v_lshl_add_u64 v[2:3], v[2:3], 0, v[192:193]
	s_mov_b64 s[28:29], 0x1600
	v_lshl_add_u64 v[6:7], v[2:3], 0, s[28:29]
	v_add_co_u32_e32 v2, vcc, s3, v2
	v_and_b32_e32 v8, 63, v0
	s_nop 0
	v_addc_co_u32_e32 v3, vcc, 0, v3, vcc
	global_load_dwordx4 v[2:5], v[2:3], off offset:1536
	global_load_dwordx4 v[12:15], v[6:7], off offset:32
	global_load_dwordx4 v[16:19], v[6:7], off offset:64
	global_load_dwordx4 v[20:23], v[6:7], off offset:96
	global_load_dwordx4 v[24:27], v[6:7], off offset:128
	global_load_dwordx4 v[28:31], v[6:7], off offset:160
	global_load_dwordx4 v[32:35], v[6:7], off offset:192
	global_load_dwordx4 v[36:39], v[6:7], off offset:224
	s_ashr_i32 s22, s4, 8
	v_lshlrev_b32_e32 v241, 2, v8
	s_mul_hi_i32 s11, s10, 0x1400000
	s_mul_i32 s10, s10, 0x1400000
	s_add_u32 s18, s18, s10
	s_addc_u32 s19, s19, s11
	s_lshl_b64 s[10:11], s[14:15], 1
	v_add_u32_e32 v40, 0x200, v0
	s_add_u32 s10, s18, s10
	v_ashrrev_i32_e32 v45, 4, v40
	v_lshlrev_b32_e32 v40, 4, v0
	s_addc_u32 s11, s19, s11
	v_and_b32_e32 v202, 0xf0, v40
	v_mov_b32_e32 v203, v193
	v_lshl_add_u64 v[40:41], s[10:11], 0, v[202:203]
	s_mov_b64 s[10:11], 0x1c00
	v_lshl_add_u64 v[204:205], v[40:41], 0, s[10:11]
	s_mov_b64 s[10:11], 0x2200
	v_lshl_add_u64 v[206:207], v[40:41], 0, s[10:11]
	v_ashrrev_i32_e32 v44, 4, v0
	v_mad_i64_i32 v[40:41], s[10:11], v45, s55, v[206:207]
	v_mad_i64_i32 v[42:43], s[10:11], v44, s55, v[206:207]
	global_load_dwordx4 v[188:191], v[40:41], off
	global_load_dwordx4 v[184:187], v[42:43], off
	v_mad_i64_i32 v[40:41], s[10:11], v45, s55, v[204:205]
	v_mad_i64_i32 v[42:43], s[10:11], v44, s55, v[204:205]
	global_load_dwordx4 v[180:183], v[40:41], off
	global_load_dwordx4 v[176:179], v[42:43], off
	s_waitcnt vmcnt(11)
	ds_write_b128 v240, v[2:5]
	s_waitcnt vmcnt(10)
	ds_write_b128 v240, v[12:15] offset:32
	s_waitcnt vmcnt(9)
	ds_write_b128 v240, v[16:19] offset:64
	s_waitcnt vmcnt(8)
	ds_write_b128 v240, v[20:23] offset:96
	s_waitcnt vmcnt(7)
	ds_write_b128 v240, v[24:27] offset:128
	s_waitcnt vmcnt(6)
	ds_write_b128 v240, v[28:31] offset:160
	s_waitcnt vmcnt(5)
	ds_write_b128 v240, v[32:35] offset:192
	s_waitcnt vmcnt(4)
	ds_write_b128 v240, v[36:39] offset:224
	s_cmp_gt_i32 s25, 47
	s_cbranch_scc1 .LBB0_603
	v_bfe_u32 v3, v0, 2, 2
	v_and_b32_e32 v4, 16, v0
	v_lshrrev_b32_e32 v0, 3, v0
	s_lshl_b32 s25, s22, 5
	v_and_b32_e32 v0, 4, v0
	v_or_b32_e32 v2, s25, v1
	v_or3_b32 v0, v0, v3, s25
	v_mad_i64_i32 v[210:211], s[10:11], v44, s55, 0
	v_mad_i64_i32 v[212:213], s[10:11], v45, s55, 0
	v_mul_lo_u32 v246, v2, s95
	v_lshlrev_b32_e32 v2, 2, v239
	v_mul_lo_u32 v247, v0, s96
	v_and_or_b32 v0, v241, 12, v4
	v_lshlrev_b32_e32 v248, 1, v0
	s_lshl_b32 s10, s20, 7
	v_sub_u32_e32 v0, v1, v2
	v_mov_b32_e32 v14, v193
	v_mov_b32_e32 v15, v193
	s_lshl_b32 s24, s24, 1
	v_mul_lo_u32 v242, v44, s95
	v_mul_lo_u32 v243, v45, s95
	v_mul_lo_u32 v244, v44, s96
	v_mul_lo_u32 v245, v45, s96
	s_or_b32 s10, s10, s21
	v_subrev_u32_e32 v249, s25, v0
	v_mov_b32_e32 v0, v193
	v_mov_b32_e32 v1, v193
	v_mov_b32_e32 v2, v193
	v_mov_b32_e32 v3, v193
	v_mov_b32_e32 v4, v193
	v_mov_b32_e32 v5, v193
	v_mov_b32_e32 v6, v193
	v_mov_b32_e32 v7, v193
	v_mov_b32_e32 v8, v193
	v_mov_b32_e32 v9, v193
	v_mov_b32_e32 v10, v193
	v_mov_b32_e32 v11, v193
	v_mov_b32_e32 v12, v193
	v_mov_b32_e32 v13, v193
	v_mov_b32_e32 v208, 0
	v_mov_b64_e32 v[46:47], v[14:15]
	v_mov_b64_e32 v[78:79], v[14:15]
	v_mov_b64_e32 v[126:127], v[14:15]
	v_mov_b64_e32 v[30:31], v[14:15]
	v_mov_b64_e32 v[62:63], v[14:15]
	v_mov_b64_e32 v[94:95], v[14:15]
	v_mov_b64_e32 v[110:111], v[14:15]
	s_add_i32 s24, s24, 2
	s_or_b32 s26, s26, 31
	s_add_i32 s27, s10, 0x741
	s_mov_b32 s28, 0
	v_mov_b32_e32 v250, 0xf149f2ca
	v_mov_b64_e32 v[44:45], v[12:13]
	v_mov_b64_e32 v[42:43], v[10:11]
	v_mov_b64_e32 v[40:41], v[8:9]
	v_mov_b64_e32 v[38:39], v[6:7]
	v_mov_b64_e32 v[36:37], v[4:5]
	v_mov_b64_e32 v[34:35], v[2:3]
	v_mov_b64_e32 v[32:33], v[0:1]
	v_mov_b64_e32 v[76:77], v[12:13]
	v_mov_b64_e32 v[74:75], v[10:11]
	v_mov_b64_e32 v[72:73], v[8:9]
	v_mov_b64_e32 v[70:71], v[6:7]
	v_mov_b64_e32 v[68:69], v[4:5]
	v_mov_b64_e32 v[66:67], v[2:3]
	v_mov_b64_e32 v[64:65], v[0:1]
	v_mov_b64_e32 v[124:125], v[12:13]
	v_mov_b64_e32 v[122:123], v[10:11]
	v_mov_b64_e32 v[120:121], v[8:9]
	v_mov_b64_e32 v[118:119], v[6:7]
	v_mov_b64_e32 v[116:117], v[4:5]
	v_mov_b64_e32 v[114:115], v[2:3]
	v_mov_b64_e32 v[112:113], v[0:1]
	v_mov_b64_e32 v[28:29], v[12:13]
	v_mov_b64_e32 v[26:27], v[10:11]
	v_mov_b64_e32 v[24:25], v[8:9]
	v_mov_b64_e32 v[22:23], v[6:7]
	v_mov_b64_e32 v[20:21], v[4:5]
	v_mov_b64_e32 v[18:19], v[2:3]
	v_mov_b64_e32 v[16:17], v[0:1]
	v_mov_b64_e32 v[60:61], v[12:13]
	v_mov_b64_e32 v[58:59], v[10:11]
	v_mov_b64_e32 v[56:57], v[8:9]
	v_mov_b64_e32 v[54:55], v[6:7]
	v_mov_b64_e32 v[52:53], v[4:5]
	v_mov_b64_e32 v[50:51], v[2:3]
	v_mov_b64_e32 v[48:49], v[0:1]
	v_mov_b64_e32 v[92:93], v[12:13]
	v_mov_b64_e32 v[90:91], v[10:11]
	v_mov_b64_e32 v[88:89], v[8:9]
	v_mov_b64_e32 v[86:87], v[6:7]
	v_mov_b64_e32 v[84:85], v[4:5]
	v_mov_b64_e32 v[82:83], v[2:3]
	v_mov_b64_e32 v[80:81], v[0:1]
	v_mov_b64_e32 v[108:109], v[12:13]
	v_mov_b64_e32 v[106:107], v[10:11]
	v_mov_b64_e32 v[104:105], v[8:9]
	v_mov_b64_e32 v[102:103], v[6:7]
	v_mov_b64_e32 v[100:101], v[4:5]
	v_mov_b64_e32 v[98:99], v[2:3]
	v_mov_b64_e32 v[96:97], v[0:1]
	s_mov_b32 s29, 0
	v_mov_b32_e32 v203, 0xf149f2ca
	v_mov_b32_e32 v209, v208
	s_branch .LBB0_528
